# P6: half-cost tiles (padding M-tile skips the ai=1 MFMA groups, logits column tile skips the bj=1 groups) permuted into the ninth partial round
# baseline (speedup 1.0000x reference)
;     __device__ bool next(int i, Unit& u) const { const bool ok = base.next(i >> 1, u); u.sub = i & 1; return ok; }
;     __device__ bool next(int i, Unit& u) const {
;         const long L = (long)i * G + c; if (L >= nwg) return false;
;         int wgid = (int)L; { const int q = nwg / NXCD, r = nwg % NXCD, xcd = wgid % NXCD, off = wgid / NXCD; wgid = (xcd < r ? xcd * (q + 1) : r * (q + 1) + (xcd - r) * q) + off; }
;         const int nig = WGM * nN, gid = wgid / nig, fm = gid * WGM, gsz = (nM - fm) < WGM ? (nM - fm) : WGM;
;         u.pm = fm + ((wgid % nig) % gsz); u.pn = (wgid % nig) / gsz; u.sub = 0; return true;
.LBB0_736:
	s_add_i32 s59, s59, 1
	s_mul_i32 s10, s59, s63
	s_mul_hi_u32 s11, s59, s64
	s_add_i32 s11, s11, s10
	s_mul_i32 s10, s59, s64
	s_add_u32 s14, s10, s2
	s_addc_u32 s15, s11, s65
	v_cmp_gt_i64_e32 vcc, s[14:15], v[148:149]
	v_cmp_lt_i64_e64 s[10:11], s[14:15], v[146:147]
	s_cbranch_vccnz .LBB0_742
	s_cmpk_lt_u32 s14, 0x31f
	s_cbranch_scc1 .Lp6_noremap
	s_mov_b32 s94, s14
	s_cmpk_lt_u32 s14, 0x800
	s_cbranch_scc1 .Lp6_btab
	s_cmpk_eq_u32 s14, 0x800
	s_cmovk_i32 s94, 0x31f
	s_cmpk_eq_u32 s14, 0x802
	s_cmovk_i32 s94, 0x327
	s_cmpk_eq_u32 s14, 0x803
	s_cmovk_i32 s94, 0x32f
	s_cmpk_eq_u32 s14, 0x804
	s_cmovk_i32 s94, 0x337
	s_cmpk_eq_u32 s14, 0x805
	s_cmovk_i32 s94, 0x33e
	s_cmpk_eq_u32 s14, 0x806
	s_cmovk_i32 s94, 0x346
	s_cmpk_eq_u32 s14, 0x808
	s_cmovk_i32 s94, 0x34e
	s_cmpk_eq_u32 s14, 0x80a
	s_cmovk_i32 s94, 0x356
	s_cmpk_eq_u32 s14, 0x80b
	s_cmovk_i32 s94, 0x35d
	s_cmpk_eq_u32 s14, 0x80c
	s_cmovk_i32 s94, 0x365
	s_cmpk_eq_u32 s14, 0x80d
	s_cmovk_i32 s94, 0x36d
	s_cmpk_eq_u32 s14, 0x80e
	s_cmovk_i32 s94, 0x375
	s_cmpk_eq_u32 s14, 0x810
	s_cmovk_i32 s94, 0x37c
	s_cmpk_eq_u32 s14, 0x812
	s_cmovk_i32 s94, 0x384
	s_cmpk_eq_u32 s14, 0x813
	s_cmovk_i32 s94, 0x38c
	s_cmpk_eq_u32 s14, 0x814
	s_cmovk_i32 s94, 0x394
	s_cmpk_eq_u32 s14, 0x815
	s_cmovk_i32 s94, 0x39b
	s_cmpk_eq_u32 s14, 0x816
	s_cmovk_i32 s94, 0x3a3
	s_cmpk_eq_u32 s14, 0x818
	s_cmovk_i32 s94, 0x3ab
	s_cmpk_eq_u32 s14, 0x819
	s_cmovk_i32 s94, 0x3b3
	s_cmpk_eq_u32 s14, 0x81a
	s_cmovk_i32 s94, 0x3ba
	s_cmpk_eq_u32 s14, 0x81b
	s_cmovk_i32 s94, 0x3c2
	s_cmpk_eq_u32 s14, 0x81c
	s_cmovk_i32 s94, 0x3ca
	s_cmpk_eq_u32 s14, 0x81d
	s_cmovk_i32 s94, 0x3d2
	s_cmpk_eq_u32 s14, 0x81e
	s_cmovk_i32 s94, 0x3d9
	s_cmpk_eq_u32 s14, 0x821
	s_cmovk_i32 s94, 0x3e1
	s_cmpk_eq_u32 s14, 0x822
	s_cmovk_i32 s94, 0x3e9
	s_cmpk_eq_u32 s14, 0x823
	s_cmovk_i32 s94, 0x3f1
	s_cmpk_eq_u32 s14, 0x824
	s_cmovk_i32 s94, 0x400
	s_cmpk_eq_u32 s14, 0x825
	s_cmovk_i32 s94, 0x408
	s_cmpk_eq_u32 s14, 0x826
	s_cmovk_i32 s94, 0x410
	s_cmpk_eq_u32 s14, 0x829
	s_cmovk_i32 s94, 0x418
	s_cmpk_eq_u32 s14, 0x82a
	s_cmovk_i32 s94, 0x73f
	s_cmpk_eq_u32 s14, 0x82b
	s_cmovk_i32 s94, 0x747
	s_cmpk_eq_u32 s14, 0x82c
	s_cmovk_i32 s94, 0x74f
	s_cmpk_eq_u32 s14, 0x82d
	s_cmovk_i32 s94, 0x757
	s_cmpk_eq_u32 s14, 0x82e
	s_cmovk_i32 s94, 0x75e
	s_cmpk_eq_u32 s14, 0x831
	s_cmovk_i32 s94, 0x75f
	s_cmpk_eq_u32 s14, 0x832
	s_cmovk_i32 s94, 0x766
	s_cmpk_eq_u32 s14, 0x833
	s_cmovk_i32 s94, 0x767
	s_cmpk_eq_u32 s14, 0x834
	s_cmovk_i32 s94, 0x76e
	s_cmpk_eq_u32 s14, 0x835
	s_cmovk_i32 s94, 0x76f
	s_cmpk_eq_u32 s14, 0x836
	s_cmovk_i32 s94, 0x776
	s_cmpk_eq_u32 s14, 0x839
	s_cmovk_i32 s94, 0x777
	s_cmpk_eq_u32 s14, 0x83a
	s_cmovk_i32 s94, 0x77d
	s_cmpk_eq_u32 s14, 0x83b
	s_cmovk_i32 s94, 0x77f
	s_cmpk_eq_u32 s14, 0x83c
	s_cmovk_i32 s94, 0x785
	s_cmpk_eq_u32 s14, 0x83d
	s_cmovk_i32 s94, 0x787
	s_cmpk_eq_u32 s14, 0x83e
	s_cmovk_i32 s94, 0x78d
	s_cmpk_eq_u32 s14, 0x840
	s_cmovk_i32 s94, 0x78f
	s_cmpk_eq_u32 s14, 0x841
	s_cmovk_i32 s94, 0x795
	s_cmpk_eq_u32 s14, 0x842
	s_cmovk_i32 s94, 0x797
	s_cmpk_eq_u32 s14, 0x843
	s_cmovk_i32 s94, 0x79c
	s_cmpk_eq_u32 s14, 0x844
	s_cmovk_i32 s94, 0x79f
	s_cmpk_eq_u32 s14, 0x845
	s_cmovk_i32 s94, 0x7a4
	s_cmpk_eq_u32 s14, 0x846
	s_cmovk_i32 s94, 0x7a7
	s_cmpk_eq_u32 s14, 0x848
	s_cmovk_i32 s94, 0x7ac
	s_cmpk_eq_u32 s14, 0x849
	s_cmovk_i32 s94, 0x7af
	s_cmpk_eq_u32 s14, 0x84a
	s_cmovk_i32 s94, 0x7b4
	s_cmpk_eq_u32 s14, 0x84b
	s_cmovk_i32 s94, 0x7b7
	s_cmpk_eq_u32 s14, 0x84c
	s_cmovk_i32 s94, 0x7bb
	s_cmpk_eq_u32 s14, 0x84d
	s_cmovk_i32 s94, 0x7bf
	s_cmpk_eq_u32 s14, 0x84e
	s_cmovk_i32 s94, 0x7c3
	s_cmpk_eq_u32 s14, 0x850
	s_cmovk_i32 s94, 0x7c7
	s_cmpk_eq_u32 s14, 0x851
	s_cmovk_i32 s94, 0x7cb
	s_cmpk_eq_u32 s14, 0x852
	s_cmovk_i32 s94, 0x7cf
	s_cmpk_eq_u32 s14, 0x853
	s_cmovk_i32 s94, 0x7d3
	s_cmpk_eq_u32 s14, 0x854
	s_cmovk_i32 s94, 0x7d7
	s_cmpk_eq_u32 s14, 0x855
	s_cmovk_i32 s94, 0x7da
	s_cmpk_eq_u32 s14, 0x856
	s_cmovk_i32 s94, 0x7df
	s_cmpk_eq_u32 s14, 0x858
	s_cmovk_i32 s94, 0x7e2
	s_cmpk_eq_u32 s14, 0x859
	s_cmovk_i32 s94, 0x7e7
	s_cmpk_eq_u32 s14, 0x85a
	s_cmovk_i32 s94, 0x7ea
	s_cmpk_eq_u32 s14, 0x85b
	s_cmovk_i32 s94, 0x7ef
	s_cmpk_eq_u32 s14, 0x85c
	s_cmovk_i32 s94, 0x7f2
	s_cmpk_eq_u32 s14, 0x85d
	s_cmovk_i32 s94, 0x7f7
	s_cmpk_eq_u32 s14, 0x85e
	s_cmovk_i32 s94, 0x7f9
	s_cmpk_eq_u32 s14, 0x860
	s_cmovk_i32 s94, 0x7ff
	s_branch .Lp6_done
;     __device__ bool next(int i, Unit& u) const { const bool ok = base.next(i >> 1, u); u.sub = i & 1; return ok; }
;     __device__ bool next(int i, Unit& u) const {
;         const long L = (long)i * G + c; if (L >= nwg) return false;
;         int wgid = (int)L; { const int q = nwg / NXCD, r = nwg % NXCD, xcd = wgid % NXCD, off = wgid / NXCD; wgid = (xcd < r ? xcd * (q + 1) : r * (q + 1) + (xcd - r) * q) + off; }
;         const int nig = WGM * nN, gid = wgid / nig, fm = gid * WGM, gsz = (nM - fm) < WGM ? (nM - fm) : WGM;
;         u.pm = fm + ((wgid % nig) % gsz); u.pn = (wgid % nig) / gsz; u.sub = 0; return true;
.Lp6_btab:
	s_cmpk_eq_u32 s14, 0x31f
	s_cmovk_i32 s94, 0x800
	s_cmpk_eq_u32 s14, 0x327
	s_cmovk_i32 s94, 0x802
	s_cmpk_eq_u32 s14, 0x32f
	s_cmovk_i32 s94, 0x803
	s_cmpk_eq_u32 s14, 0x337
	s_cmovk_i32 s94, 0x804
	s_cmpk_eq_u32 s14, 0x33e
	s_cmovk_i32 s94, 0x805
	s_cmpk_eq_u32 s14, 0x346
	s_cmovk_i32 s94, 0x806
	s_cmpk_eq_u32 s14, 0x34e
	s_cmovk_i32 s94, 0x808
	s_cmpk_eq_u32 s14, 0x356
	s_cmovk_i32 s94, 0x80a
	s_cmpk_eq_u32 s14, 0x35d
	s_cmovk_i32 s94, 0x80b
	s_cmpk_eq_u32 s14, 0x365
	s_cmovk_i32 s94, 0x80c
	s_cmpk_eq_u32 s14, 0x36d
	s_cmovk_i32 s94, 0x80d
	s_cmpk_eq_u32 s14, 0x375
	s_cmovk_i32 s94, 0x80e
	s_cmpk_eq_u32 s14, 0x37c
	s_cmovk_i32 s94, 0x810
	s_cmpk_eq_u32 s14, 0x384
	s_cmovk_i32 s94, 0x812
	s_cmpk_eq_u32 s14, 0x38c
	s_cmovk_i32 s94, 0x813
	s_cmpk_eq_u32 s14, 0x394
	s_cmovk_i32 s94, 0x814
	s_cmpk_eq_u32 s14, 0x39b
	s_cmovk_i32 s94, 0x815
	s_cmpk_eq_u32 s14, 0x3a3
	s_cmovk_i32 s94, 0x816
	s_cmpk_eq_u32 s14, 0x3ab
	s_cmovk_i32 s94, 0x818
	s_cmpk_eq_u32 s14, 0x3b3
	s_cmovk_i32 s94, 0x819
	s_cmpk_eq_u32 s14, 0x3ba
	s_cmovk_i32 s94, 0x81a
	s_cmpk_eq_u32 s14, 0x3c2
	s_cmovk_i32 s94, 0x81b
	s_cmpk_eq_u32 s14, 0x3ca
	s_cmovk_i32 s94, 0x81c
	s_cmpk_eq_u32 s14, 0x3d2
	s_cmovk_i32 s94, 0x81d
	s_cmpk_eq_u32 s14, 0x3d9
	s_cmovk_i32 s94, 0x81e
	s_cmpk_eq_u32 s14, 0x3e1
	s_cmovk_i32 s94, 0x821
	s_cmpk_eq_u32 s14, 0x3e9
	s_cmovk_i32 s94, 0x822
	s_cmpk_eq_u32 s14, 0x3f1
	s_cmovk_i32 s94, 0x823
	s_cmpk_eq_u32 s14, 0x400
	s_cmovk_i32 s94, 0x824
	s_cmpk_eq_u32 s14, 0x408
	s_cmovk_i32 s94, 0x825
	s_cmpk_eq_u32 s14, 0x410
	s_cmovk_i32 s94, 0x826
	s_cmpk_eq_u32 s14, 0x418
	s_cmovk_i32 s94, 0x829
	s_cmpk_eq_u32 s14, 0x73f
	s_cmovk_i32 s94, 0x82a
	s_cmpk_eq_u32 s14, 0x747
	s_cmovk_i32 s94, 0x82b
	s_cmpk_eq_u32 s14, 0x74f
	s_cmovk_i32 s94, 0x82c
	s_cmpk_eq_u32 s14, 0x757
	s_cmovk_i32 s94, 0x82d
	s_cmpk_eq_u32 s14, 0x75e
	s_cmovk_i32 s94, 0x82e
	s_cmpk_eq_u32 s14, 0x75f
	s_cmovk_i32 s94, 0x831
	s_cmpk_eq_u32 s14, 0x766
	s_cmovk_i32 s94, 0x832
	s_cmpk_eq_u32 s14, 0x767
	s_cmovk_i32 s94, 0x833
	s_cmpk_eq_u32 s14, 0x76e
	s_cmovk_i32 s94, 0x834
	s_cmpk_eq_u32 s14, 0x76f
	s_cmovk_i32 s94, 0x835
	s_cmpk_eq_u32 s14, 0x776
	s_cmovk_i32 s94, 0x836
	s_cmpk_eq_u32 s14, 0x777
	s_cmovk_i32 s94, 0x839
	s_cmpk_eq_u32 s14, 0x77d
	s_cmovk_i32 s94, 0x83a
	s_cmpk_eq_u32 s14, 0x77f
	s_cmovk_i32 s94, 0x83b
	s_cmpk_eq_u32 s14, 0x785
	s_cmovk_i32 s94, 0x83c
	s_cmpk_eq_u32 s14, 0x787
	s_cmovk_i32 s94, 0x83d
	s_cmpk_eq_u32 s14, 0x78d
	s_cmovk_i32 s94, 0x83e
	s_cmpk_eq_u32 s14, 0x78f
	s_cmovk_i32 s94, 0x840
	s_cmpk_eq_u32 s14, 0x795
	s_cmovk_i32 s94, 0x841
	s_cmpk_eq_u32 s14, 0x797
	s_cmovk_i32 s94, 0x842
	s_cmpk_eq_u32 s14, 0x79c
	s_cmovk_i32 s94, 0x843
	s_cmpk_eq_u32 s14, 0x79f
	s_cmovk_i32 s94, 0x844
	s_cmpk_eq_u32 s14, 0x7a4
	s_cmovk_i32 s94, 0x845
	s_cmpk_eq_u32 s14, 0x7a7
	s_cmovk_i32 s94, 0x846
	s_cmpk_eq_u32 s14, 0x7ac
	s_cmovk_i32 s94, 0x848
	s_cmpk_eq_u32 s14, 0x7af
	s_cmovk_i32 s94, 0x849
	s_cmpk_eq_u32 s14, 0x7b4
	s_cmovk_i32 s94, 0x84a
	s_cmpk_eq_u32 s14, 0x7b7
	s_cmovk_i32 s94, 0x84b
	s_cmpk_eq_u32 s14, 0x7bb
	s_cmovk_i32 s94, 0x84c
	s_cmpk_eq_u32 s14, 0x7bf
	s_cmovk_i32 s94, 0x84d
	s_cmpk_eq_u32 s14, 0x7c3
	s_cmovk_i32 s94, 0x84e
	s_cmpk_eq_u32 s14, 0x7c7
	s_cmovk_i32 s94, 0x850
	s_cmpk_eq_u32 s14, 0x7cb
	s_cmovk_i32 s94, 0x851
	s_cmpk_eq_u32 s14, 0x7cf
	s_cmovk_i32 s94, 0x852
	s_cmpk_eq_u32 s14, 0x7d3
	s_cmovk_i32 s94, 0x853
	s_cmpk_eq_u32 s14, 0x7d7
	s_cmovk_i32 s94, 0x854
	s_cmpk_eq_u32 s14, 0x7da
	s_cmovk_i32 s94, 0x855
	s_cmpk_eq_u32 s14, 0x7df
	s_cmovk_i32 s94, 0x856
	s_cmpk_eq_u32 s14, 0x7e2
	s_cmovk_i32 s94, 0x858
	s_cmpk_eq_u32 s14, 0x7e7
	s_cmovk_i32 s94, 0x859
	s_cmpk_eq_u32 s14, 0x7ea
	s_cmovk_i32 s94, 0x85a
	s_cmpk_eq_u32 s14, 0x7ef
	s_cmovk_i32 s94, 0x85b
	s_cmpk_eq_u32 s14, 0x7f2
	s_cmovk_i32 s94, 0x85c
	s_cmpk_eq_u32 s14, 0x7f7
	s_cmovk_i32 s94, 0x85d
	s_cmpk_eq_u32 s14, 0x7f9
	s_cmovk_i32 s94, 0x85e
	s_cmpk_eq_u32 s14, 0x7ff
	s_cmovk_i32 s94, 0x860
.Lp6_done:
	s_mov_b32 s14, s94
.Lp6_noremap:
	s_ashr_i32 s13, s14, 31
	s_lshr_b32 s13, s13, 29
	s_add_i32 s13, s14, s13
	s_and_b32 s15, s13, -8
	s_sub_i32 s34, s14, s15
	s_cmp_gt_i32 s34, 0
	s_mov_b64 s[14:15], -1
	s_cbranch_scc0 .LBB0_739
	s_mul_i32 s14, s34, 0x10c
	s_or_b32 s35, s14, 1
	s_mov_b64 s[14:15], 0

; #define PG8_STAGE(bufoff, gbase, voff) do { _Pragma("unroll") for (int _i = 0; _i < 2; ++_i) \
;         __builtin_amdgcn_global_load_lds((const unsigned*)((const char*)(gbase) + (voff)[_i]), (LAS unsigned*)(lds + (bufoff) + ldsw + _i * 8192), 16, 0, 0); } while (0)
; #define PG8_LDA(dst, b, h) do { _Pragma("unroll") for (int m = 0; m < 4; ++m) _Pragma("unroll") for (int k = 0; k < 2; ++k) dst[m][k] = *(const LAS bf16x8*)(lds + PG8_SA(b, h) + aoff + m * 2048 + k * 1024); } while (0)
; #define PG8_LDB(dst, b, h) do { _Pragma("unroll") for (int n = 0; n < 2; ++n) _Pragma("unroll") for (int k = 0; k < 2; ++k) dst[n][k] = *(const LAS bf16x8*)(lds + PG8_SB(b, h) + boff + n * 2048 + k * 1024); } while (0)
; #define PG8_MMA(ai, bj, At, Bt) do { __builtin_amdgcn_s_setprio(1); _Pragma("unroll") for (int m = 0; m < 4; ++m) _Pragma("unroll") for (int n = 0; n < 2; ++n) _Pragma("unroll") for (int k = 0; k < 2; ++k) \
;         acc[ai][bj][m][n] = __builtin_amdgcn_mfma_f32_16x16x32_bf16(Bt[n][k], At[m][k], acc[ai][bj][m][n], 0, 0, 0); __builtin_amdgcn_s_setprio(0); } while (0)
; #define PG8_WAIT_V(n) asm volatile("s_waitcnt vmcnt(" #n ")" ::: "memory")
; #define PG8_WAIT_L(n) asm volatile("s_waitcnt lgkmcnt(" #n ")" ::: "memory")
; #define PG8_BAR __builtin_amdgcn_s_barrier()
; #define PG8_SCHED __builtin_amdgcn_sched_barrier(0)
; template <class Epi, class Sched>
; __device__ __forceinline__ void gemm_phase(LAS unsigned char* lds, const Gemm g, const Sched& S, const Epi& E, int wid) {
;     ...
;             PG8_LDB(B0, 0, 0); PG8_LDB(B1, 0, 1); PG8_SCHED; PG8_LDA(At, 0, 0); PG8_STAGE(PG8_SA(1, 1), a1 + hstep, voffA);
;             PG8_WAIT_V(8); PG8_WAIT_L(0); PG8_BAR; PG8_MMA(0, 0, At, B0); PG8_MMA(0, 1, At, B1); PG8_BAR; PG8_SCHED;
;             PG8_LDA(At, 0, 1); PG8_STAGE(PG8_SB(0, 0), b2, voffB); PG8_STAGE(PG8_SB(0, 1), b2 + hstep, voffB); PG8_STAGE(PG8_SA(0, 0), a2, voffA);
;             PG8_WAIT_V(8); PG8_WAIT_L(0); PG8_BAR; PG8_MMA(1, 0, At, B0); PG8_MMA(1, 1, At, B1); PG8_BAR; PG8_SCHED;
.LBB0_743:
	ds_read_b128 v[150:153], v172
	ds_read_b128 v[154:157], v172 offset:1024
	ds_read_b128 v[158:161], v172 offset:2048
	ds_read_b128 v[162:165], v172 offset:3072
	ds_read_b128 v[176:179], v173
	ds_read_b128 v[180:183], v173 offset:1024
	ds_read_b128 v[184:187], v173 offset:2048
	ds_read_b128 v[188:191], v173 offset:3072
	s_add_u32 s4, s6, 0xfffc0080
	s_addc_u32 s5, s7, -1
	s_cmp_eq_u32 s45, 12
	s_cselect_b32 s15, s13, s5
	s_cselect_b32 s14, s37, s4
	s_cselect_b32 s5, s35, s44
	s_cselect_b32 s4, s42, s43
	v_lshl_add_u64 v[224:225], s[6:7], 0, v[142:143]
	s_add_i32 m0, s23, 0xc000
	ds_read_b128 v[192:195], v174
	ds_read_b128 v[196:199], v174 offset:1024
	ds_read_b128 v[200:203], v174 offset:2048
	ds_read_b128 v[204:207], v174 offset:3072
	ds_read_b128 v[208:211], v174 offset:4096
	ds_read_b128 v[212:215], v174 offset:5120
	ds_read_b128 v[216:219], v174 offset:6144
	ds_read_b128 v[220:223], v174 offset:7168
	global_load_lds_dwordx4 v[224:225], off
	v_lshl_add_u64 v[224:225], s[6:7], 0, v[144:145]
	s_add_i32 m0, s23, 0xe000
	s_nop 0
	global_load_lds_dwordx4 v[224:225], off
	s_waitcnt vmcnt(8)
	s_waitcnt lgkmcnt(0)
	s_barrier
	s_setprio 1
	s_waitcnt lgkmcnt(0)
	v_mfma_f32_16x16x32_bf16 v[60:63], v[150:153], v[192:195], v[60:63]
	v_mfma_f32_16x16x32_bf16 v[56:59], v[158:161], v[192:195], v[56:59]
	v_mfma_f32_16x16x32_bf16 v[52:55], v[150:153], v[200:203], v[52:55]
	v_mfma_f32_16x16x32_bf16 v[48:51], v[158:161], v[200:203], v[48:51]
	v_mfma_f32_16x16x32_bf16 v[44:47], v[150:153], v[208:211], v[44:47]
	v_mfma_f32_16x16x32_bf16 v[40:43], v[158:161], v[208:211], v[40:43]
	v_mfma_f32_16x16x32_bf16 v[36:39], v[150:153], v[216:219], v[36:39]
	v_mfma_f32_16x16x32_bf16 v[32:35], v[158:161], v[216:219], v[32:35]
	v_mfma_f32_16x16x32_bf16 v[60:63], v[154:157], v[196:199], v[60:63]
	v_mfma_f32_16x16x32_bf16 v[56:59], v[162:165], v[196:199], v[56:59]
	v_mfma_f32_16x16x32_bf16 v[52:55], v[154:157], v[204:207], v[52:55]
	v_mfma_f32_16x16x32_bf16 v[48:51], v[162:165], v[204:207], v[48:51]
	v_mfma_f32_16x16x32_bf16 v[44:47], v[154:157], v[212:215], v[44:47]
	v_mfma_f32_16x16x32_bf16 v[40:43], v[162:165], v[212:215], v[40:43]
	v_mfma_f32_16x16x32_bf16 v[36:39], v[154:157], v[220:223], v[36:39]
	v_mfma_f32_16x16x32_bf16 v[32:35], v[162:165], v[220:223], v[32:35]
	s_setprio 0
	s_cmp_eq_u32 s12, 32
	s_cbranch_scc1 .Lp6k_1
	s_setprio 1
	v_mfma_f32_16x16x32_bf16 v[124:127], v[176:179], v[192:195], v[124:127]
	v_mfma_f32_16x16x32_bf16 v[120:123], v[184:187], v[192:195], v[120:123]
	v_mfma_f32_16x16x32_bf16 v[116:119], v[176:179], v[200:203], v[116:119]
	v_mfma_f32_16x16x32_bf16 v[112:115], v[184:187], v[200:203], v[112:115]
	v_mfma_f32_16x16x32_bf16 v[108:111], v[176:179], v[208:211], v[108:111]
	v_mfma_f32_16x16x32_bf16 v[104:107], v[184:187], v[208:211], v[104:107]
	v_mfma_f32_16x16x32_bf16 v[100:103], v[176:179], v[216:219], v[100:103]
	v_mfma_f32_16x16x32_bf16 v[96:99], v[184:187], v[216:219], v[96:99]
	v_mfma_f32_16x16x32_bf16 v[124:127], v[180:183], v[196:199], v[124:127]
	v_mfma_f32_16x16x32_bf16 v[120:123], v[188:191], v[196:199], v[120:123]
	v_mfma_f32_16x16x32_bf16 v[116:119], v[180:183], v[204:207], v[116:119]
	v_mfma_f32_16x16x32_bf16 v[112:115], v[188:191], v[204:207], v[112:115]
	v_mfma_f32_16x16x32_bf16 v[108:111], v[180:183], v[212:215], v[108:111]
	v_mfma_f32_16x16x32_bf16 v[104:107], v[188:191], v[212:215], v[104:107]
	v_mfma_f32_16x16x32_bf16 v[100:103], v[180:183], v[220:223], v[100:103]
	v_mfma_f32_16x16x32_bf16 v[96:99], v[188:191], v[220:223], v[96:99]
	s_setprio 0
.Lp6k_1:
	s_barrier
	s_add_i32 s46, s66, s75
	v_lshl_add_u64 v[224:225], s[4:5], 0, v[130:131]
	s_mov_b32 m0, s46
	ds_read_b128 v[192:195], v174 offset:16384
	ds_read_b128 v[196:199], v174 offset:17408
	ds_read_b128 v[200:203], v174 offset:18432
	ds_read_b128 v[204:207], v174 offset:19456
	ds_read_b128 v[208:211], v174 offset:20480
	ds_read_b128 v[212:215], v174 offset:21504
	ds_read_b128 v[216:219], v174 offset:22528
	ds_read_b128 v[220:223], v174 offset:23552
	global_load_lds_dwordx4 v[224:225], off
	s_add_i32 m0, s46, 0x2000
	s_add_u32 s46, s4, 0x40000
	v_lshl_add_u64 v[226:227], s[4:5], 0, v[134:135]
	s_addc_u32 s47, s5, 0
	s_add_i32 s48, s67, s75
	global_load_lds_dwordx4 v[226:227], off
	v_lshl_add_u64 v[228:229], s[46:47], 0, v[130:131]
	s_mov_b32 m0, s48
	v_lshl_add_u64 v[230:231], s[14:15], 0, v[132:133]
	global_load_lds_dwordx4 v[228:229], off
	v_lshl_add_u64 v[228:229], s[46:47], 0, v[134:135]
	s_add_i32 m0, s48, 0x2000
	s_nop 0
	global_load_lds_dwordx4 v[228:229], off
	v_lshl_add_u64 v[228:229], s[14:15], 0, v[128:129]
	s_mov_b32 m0, s23
	s_nop 0
	global_load_lds_dwordx4 v[228:229], off
	s_mov_b32 m0, s56
	s_nop 0
	global_load_lds_dwordx4 v[230:231], off
	s_waitcnt vmcnt(8)
	s_waitcnt lgkmcnt(0)
	s_barrier
	s_cmp_eq_u32 s22, 64
	s_cbranch_scc1 .Lp6k_2
	s_setprio 1
	s_waitcnt lgkmcnt(0)
	v_mfma_f32_16x16x32_bf16 v[28:31], v[150:153], v[192:195], v[28:31]
	v_mfma_f32_16x16x32_bf16 v[24:27], v[158:161], v[192:195], v[24:27]
	v_mfma_f32_16x16x32_bf16 v[20:23], v[150:153], v[200:203], v[20:23]
	v_mfma_f32_16x16x32_bf16 v[16:19], v[158:161], v[200:203], v[16:19]
	v_mfma_f32_16x16x32_bf16 v[12:15], v[150:153], v[208:211], v[12:15]
	v_mfma_f32_16x16x32_bf16 v[8:11], v[158:161], v[208:211], v[8:11]
	v_mfma_f32_16x16x32_bf16 v[4:7], v[150:153], v[216:219], v[4:7]
	v_mfma_f32_16x16x32_bf16 v[0:3], v[158:161], v[216:219], v[0:3]
	v_mfma_f32_16x16x32_bf16 v[28:31], v[154:157], v[196:199], v[28:31]
	v_mfma_f32_16x16x32_bf16 v[24:27], v[162:165], v[196:199], v[24:27]
	v_mfma_f32_16x16x32_bf16 v[20:23], v[154:157], v[204:207], v[20:23]
	v_mfma_f32_16x16x32_bf16 v[16:19], v[162:165], v[204:207], v[16:19]
	v_mfma_f32_16x16x32_bf16 v[12:15], v[154:157], v[212:215], v[12:15]
	v_mfma_f32_16x16x32_bf16 v[8:11], v[162:165], v[212:215], v[8:11]
	v_mfma_f32_16x16x32_bf16 v[4:7], v[154:157], v[220:223], v[4:7]
	v_mfma_f32_16x16x32_bf16 v[0:3], v[162:165], v[220:223], v[0:3]
	s_setprio 0
	s_cmp_eq_u32 s12, 32
	s_cbranch_scc1 .Lp6k_2
; #define PG8_STAGE(bufoff, gbase, voff) do { _Pragma("unroll") for (int _i = 0; _i < 2; ++_i) \
;         __builtin_amdgcn_global_load_lds((const unsigned*)((const char*)(gbase) + (voff)[_i]), (LAS unsigned*)(lds + (bufoff) + ldsw + _i * 8192), 16, 0, 0); } while (0)
; #define PG8_LDA(dst, b, h) do { _Pragma("unroll") for (int m = 0; m < 4; ++m) _Pragma("unroll") for (int k = 0; k < 2; ++k) dst[m][k] = *(const LAS bf16x8*)(lds + PG8_SA(b, h) + aoff + m * 2048 + k * 1024); } while (0)
; #define PG8_LDB(dst, b, h) do { _Pragma("unroll") for (int n = 0; n < 2; ++n) _Pragma("unroll") for (int k = 0; k < 2; ++k) dst[n][k] = *(const LAS bf16x8*)(lds + PG8_SB(b, h) + boff + n * 2048 + k * 1024); } while (0)
; #define PG8_MMA(ai, bj, At, Bt) do { __builtin_amdgcn_s_setprio(1); _Pragma("unroll") for (int m = 0; m < 4; ++m) _Pragma("unroll") for (int n = 0; n < 2; ++n) _Pragma("unroll") for (int k = 0; k < 2; ++k) \
;         acc[ai][bj][m][n] = __builtin_amdgcn_mfma_f32_16x16x32_bf16(Bt[n][k], At[m][k], acc[ai][bj][m][n], 0, 0, 0); __builtin_amdgcn_s_setprio(0); } while (0)
; #define PG8_WAIT_V(n) asm volatile("s_waitcnt vmcnt(" #n ")" ::: "memory")
; #define PG8_WAIT_L(n) asm volatile("s_waitcnt lgkmcnt(" #n ")" ::: "memory")
; #define PG8_BAR __builtin_amdgcn_s_barrier()
; #define PG8_SCHED __builtin_amdgcn_sched_barrier(0)
; template <class Epi, class Sched>
; __device__ __forceinline__ void gemm_phase(LAS unsigned char* lds, const Gemm g, const Sched& S, const Epi& E, int wid) {
;     ...
;             PG8_WAIT_V(8); PG8_WAIT_L(0); PG8_BAR; PG8_MMA(1, 0, At, B0); PG8_MMA(1, 1, At, B1); PG8_BAR; PG8_SCHED;
;             PG8_LDB(B0, 1, 0); PG8_LDB(B1, 1, 1); PG8_SCHED; PG8_LDA(At, 1, 0); PG8_STAGE(PG8_SA(0, 1), a2 + hstep, voffA);
;             PG8_WAIT_V(8); PG8_WAIT_L(0); PG8_BAR; PG8_MMA(0, 0, At, B0); PG8_MMA(0, 1, At, B1); PG8_BAR; PG8_SCHED;
	s_setprio 1
	v_mfma_f32_16x16x32_bf16 v[92:95], v[176:179], v[192:195], v[92:95]
	v_mfma_f32_16x16x32_bf16 v[88:91], v[184:187], v[192:195], v[88:91]
	v_mfma_f32_16x16x32_bf16 v[84:87], v[176:179], v[200:203], v[84:87]
	v_mfma_f32_16x16x32_bf16 v[80:83], v[184:187], v[200:203], v[80:83]
	v_mfma_f32_16x16x32_bf16 v[76:79], v[176:179], v[208:211], v[76:79]
	v_mfma_f32_16x16x32_bf16 v[72:75], v[184:187], v[208:211], v[72:75]
	v_mfma_f32_16x16x32_bf16 v[68:71], v[176:179], v[216:219], v[68:71]
	v_mfma_f32_16x16x32_bf16 v[64:67], v[184:187], v[216:219], v[64:67]
	v_mfma_f32_16x16x32_bf16 v[92:95], v[180:183], v[196:199], v[92:95]
	v_mfma_f32_16x16x32_bf16 v[88:91], v[188:191], v[196:199], v[88:91]
	v_mfma_f32_16x16x32_bf16 v[84:87], v[180:183], v[204:207], v[84:87]
	v_mfma_f32_16x16x32_bf16 v[80:83], v[188:191], v[204:207], v[80:83]
	v_mfma_f32_16x16x32_bf16 v[76:79], v[180:183], v[212:215], v[76:79]
	v_mfma_f32_16x16x32_bf16 v[72:75], v[188:191], v[212:215], v[72:75]
	v_mfma_f32_16x16x32_bf16 v[68:71], v[180:183], v[220:223], v[68:71]
	v_mfma_f32_16x16x32_bf16 v[64:67], v[188:191], v[220:223], v[64:67]
	s_setprio 0
.Lp6k_2:
	s_barrier
	s_add_i32 s46, 0, 0x18000
	v_add_u32_e32 v136, s46, v170
	s_add_i32 s47, 0, 0x1c000
	ds_read_b128 v[150:153], v136
	ds_read_b128 v[154:157], v136 offset:1024
	ds_read_b128 v[158:161], v136 offset:2048
	ds_read_b128 v[162:165], v136 offset:3072
	v_add_u32_e32 v136, s47, v170
	ds_read_b128 v[176:179], v136
	ds_read_b128 v[180:183], v136 offset:1024
	ds_read_b128 v[184:187], v136 offset:2048
	ds_read_b128 v[188:191], v136 offset:3072
	s_add_u32 s14, s14, 0x40000
	s_addc_u32 s15, s15, 0
	s_mov_b32 m0, s57
	v_lshl_add_u64 v[232:233], s[14:15], 0, v[128:129]
	ds_read_b128 v[192:195], v174 offset:32768
	ds_read_b128 v[196:199], v174 offset:33792
	ds_read_b128 v[200:203], v174 offset:34816
	ds_read_b128 v[204:207], v174 offset:35840
	ds_read_b128 v[208:211], v174 offset:36864
	ds_read_b128 v[212:215], v174 offset:37888
	ds_read_b128 v[216:219], v174 offset:38912
	ds_read_b128 v[220:223], v174 offset:39936
	global_load_lds_dwordx4 v[232:233], off
	v_lshl_add_u64 v[232:233], s[14:15], 0, v[132:133]
	s_mov_b32 m0, s58
	s_nop 0
	global_load_lds_dwordx4 v[232:233], off
	s_waitcnt vmcnt(8)
	s_waitcnt lgkmcnt(0)
	s_barrier
	s_setprio 1
	s_waitcnt lgkmcnt(0)
	v_mfma_f32_16x16x32_bf16 v[60:63], v[150:153], v[192:195], v[60:63]
	v_mfma_f32_16x16x32_bf16 v[56:59], v[158:161], v[192:195], v[56:59]
	v_mfma_f32_16x16x32_bf16 v[52:55], v[150:153], v[200:203], v[52:55]
	v_mfma_f32_16x16x32_bf16 v[48:51], v[158:161], v[200:203], v[48:51]
	v_mfma_f32_16x16x32_bf16 v[44:47], v[150:153], v[208:211], v[44:47]
	v_mfma_f32_16x16x32_bf16 v[40:43], v[158:161], v[208:211], v[40:43]
	v_mfma_f32_16x16x32_bf16 v[36:39], v[150:153], v[216:219], v[36:39]
	v_mfma_f32_16x16x32_bf16 v[32:35], v[158:161], v[216:219], v[32:35]
	v_mfma_f32_16x16x32_bf16 v[60:63], v[154:157], v[196:199], v[60:63]
	v_mfma_f32_16x16x32_bf16 v[56:59], v[162:165], v[196:199], v[56:59]
	v_mfma_f32_16x16x32_bf16 v[52:55], v[154:157], v[204:207], v[52:55]
	v_mfma_f32_16x16x32_bf16 v[48:51], v[162:165], v[204:207], v[48:51]
	v_mfma_f32_16x16x32_bf16 v[44:47], v[154:157], v[212:215], v[44:47]
	v_mfma_f32_16x16x32_bf16 v[40:43], v[162:165], v[212:215], v[40:43]
	v_mfma_f32_16x16x32_bf16 v[36:39], v[154:157], v[220:223], v[36:39]
	v_mfma_f32_16x16x32_bf16 v[32:35], v[162:165], v[220:223], v[32:35]
	s_setprio 0
	s_cmp_eq_u32 s12, 32
	s_cbranch_scc1 .Lp6k_3
	s_setprio 1
	v_mfma_f32_16x16x32_bf16 v[124:127], v[176:179], v[192:195], v[124:127]
	v_mfma_f32_16x16x32_bf16 v[120:123], v[184:187], v[192:195], v[120:123]
	v_mfma_f32_16x16x32_bf16 v[116:119], v[176:179], v[200:203], v[116:119]
	v_mfma_f32_16x16x32_bf16 v[112:115], v[184:187], v[200:203], v[112:115]
	v_mfma_f32_16x16x32_bf16 v[108:111], v[176:179], v[208:211], v[108:111]
	v_mfma_f32_16x16x32_bf16 v[104:107], v[184:187], v[208:211], v[104:107]
	v_mfma_f32_16x16x32_bf16 v[100:103], v[176:179], v[216:219], v[100:103]
	v_mfma_f32_16x16x32_bf16 v[96:99], v[184:187], v[216:219], v[96:99]
	v_mfma_f32_16x16x32_bf16 v[124:127], v[180:183], v[196:199], v[124:127]
	v_mfma_f32_16x16x32_bf16 v[120:123], v[188:191], v[196:199], v[120:123]
	v_mfma_f32_16x16x32_bf16 v[116:119], v[180:183], v[204:207], v[116:119]
	v_mfma_f32_16x16x32_bf16 v[112:115], v[188:191], v[204:207], v[112:115]
	v_mfma_f32_16x16x32_bf16 v[108:111], v[180:183], v[212:215], v[108:111]
	v_mfma_f32_16x16x32_bf16 v[104:107], v[188:191], v[212:215], v[104:107]
	v_mfma_f32_16x16x32_bf16 v[100:103], v[180:183], v[220:223], v[100:103]
	v_mfma_f32_16x16x32_bf16 v[96:99], v[188:191], v[220:223], v[96:99]
	s_setprio 0
; #define PG8_STAGE(bufoff, gbase, voff) do { _Pragma("unroll") for (int _i = 0; _i < 2; ++_i) \
;         __builtin_amdgcn_global_load_lds((const unsigned*)((const char*)(gbase) + (voff)[_i]), (LAS unsigned*)(lds + (bufoff) + ldsw + _i * 8192), 16, 0, 0); } while (0)
; #define PG8_LDA(dst, b, h) do { _Pragma("unroll") for (int m = 0; m < 4; ++m) _Pragma("unroll") for (int k = 0; k < 2; ++k) dst[m][k] = *(const LAS bf16x8*)(lds + PG8_SA(b, h) + aoff + m * 2048 + k * 1024); } while (0)
; #define PG8_MMA(ai, bj, At, Bt) do { __builtin_amdgcn_s_setprio(1); _Pragma("unroll") for (int m = 0; m < 4; ++m) _Pragma("unroll") for (int n = 0; n < 2; ++n) _Pragma("unroll") for (int k = 0; k < 2; ++k) \
;         acc[ai][bj][m][n] = __builtin_amdgcn_mfma_f32_16x16x32_bf16(Bt[n][k], At[m][k], acc[ai][bj][m][n], 0, 0, 0); __builtin_amdgcn_s_setprio(0); } while (0)
; #define PG8_WAIT_V(n) asm volatile("s_waitcnt vmcnt(" #n ")" ::: "memory")
; #define PG8_WAIT_L(n) asm volatile("s_waitcnt lgkmcnt(" #n ")" ::: "memory")
; #define PG8_BAR __builtin_amdgcn_s_barrier()
; #define PG8_SCHED __builtin_amdgcn_sched_barrier(0)
; template <class Epi, class Sched>
; __device__ __forceinline__ void gemm_phase(LAS unsigned char* lds, const Gemm g, const Sched& S, const Epi& E, int wid) {
;     ...
;             PG8_LDA(At, 1, 1); PG8_STAGE(PG8_SB(1, 0), b3, voffB); PG8_STAGE(PG8_SB(1, 1), b3 + hstep, voffB); PG8_STAGE(PG8_SA(1, 0), a3, voffA);
;             PG8_WAIT_V(8); PG8_WAIT_L(0); PG8_BAR; PG8_MMA(1, 0, At, B0); PG8_MMA(1, 1, At, B1); PG8_BAR; PG8_SCHED;
.Lp6k_3:
	s_barrier
	s_add_i32 s14, s46, s75
	v_lshl_add_u64 v[224:225], v[224:225], 0, s[20:21]
	s_mov_b32 m0, s14
	ds_read_b128 v[192:195], v174 offset:49152
	ds_read_b128 v[196:199], v174 offset:50176
	ds_read_b128 v[200:203], v174 offset:51200
	ds_read_b128 v[204:207], v174 offset:52224
	ds_read_b128 v[208:211], v174 offset:53248
	ds_read_b128 v[212:215], v174 offset:54272
	ds_read_b128 v[216:219], v174 offset:55296
	ds_read_b128 v[220:223], v174 offset:56320
	global_load_lds_dwordx4 v[224:225], off
	s_add_i32 m0, s14, 0x2000
	s_add_u32 s4, s4, 0x40080
	v_lshl_add_u64 v[224:225], v[226:227], 0, s[20:21]
	s_addc_u32 s5, s5, 0
	s_add_i32 s14, s47, s75
	global_load_lds_dwordx4 v[224:225], off
	v_lshl_add_u64 v[224:225], s[4:5], 0, v[130:131]
	s_mov_b32 m0, s14
	s_nop 0
	global_load_lds_dwordx4 v[224:225], off
	v_lshl_add_u64 v[224:225], s[4:5], 0, v[134:135]
	s_add_i32 m0, s14, 0x2000
	s_nop 0
	global_load_lds_dwordx4 v[224:225], off
	v_lshl_add_u64 v[224:225], v[228:229], 0, s[20:21]
	s_mov_b32 m0, s61
	s_nop 0
	global_load_lds_dwordx4 v[224:225], off
	v_lshl_add_u64 v[224:225], v[230:231], 0, s[20:21]
	s_mov_b32 m0, s62
	s_nop 0
	global_load_lds_dwordx4 v[224:225], off
	s_waitcnt vmcnt(8)
	s_waitcnt lgkmcnt(0)
	s_barrier
	s_cmp_eq_u32 s22, 64
	s_cbranch_scc1 .Lp6k_4
	s_setprio 1
	s_waitcnt lgkmcnt(0)
	v_mfma_f32_16x16x32_bf16 v[28:31], v[150:153], v[192:195], v[28:31]
	v_mfma_f32_16x16x32_bf16 v[24:27], v[158:161], v[192:195], v[24:27]
	v_mfma_f32_16x16x32_bf16 v[20:23], v[150:153], v[200:203], v[20:23]
	v_mfma_f32_16x16x32_bf16 v[16:19], v[158:161], v[200:203], v[16:19]
	v_mfma_f32_16x16x32_bf16 v[12:15], v[150:153], v[208:211], v[12:15]
	v_mfma_f32_16x16x32_bf16 v[8:11], v[158:161], v[208:211], v[8:11]
	v_mfma_f32_16x16x32_bf16 v[4:7], v[150:153], v[216:219], v[4:7]
	v_mfma_f32_16x16x32_bf16 v[0:3], v[158:161], v[216:219], v[0:3]
	v_mfma_f32_16x16x32_bf16 v[28:31], v[154:157], v[196:199], v[28:31]
	v_mfma_f32_16x16x32_bf16 v[24:27], v[162:165], v[196:199], v[24:27]
	v_mfma_f32_16x16x32_bf16 v[20:23], v[154:157], v[204:207], v[20:23]
	v_mfma_f32_16x16x32_bf16 v[16:19], v[162:165], v[204:207], v[16:19]
	v_mfma_f32_16x16x32_bf16 v[12:15], v[154:157], v[212:215], v[12:15]
	v_mfma_f32_16x16x32_bf16 v[8:11], v[162:165], v[212:215], v[8:11]
	v_mfma_f32_16x16x32_bf16 v[4:7], v[154:157], v[220:223], v[4:7]
	v_mfma_f32_16x16x32_bf16 v[0:3], v[162:165], v[220:223], v[0:3]
	s_setprio 0
	s_cmp_eq_u32 s12, 32
	s_cbranch_scc1 .Lp6k_4
	s_setprio 1
	v_mfma_f32_16x16x32_bf16 v[92:95], v[176:179], v[192:195], v[92:95]
	v_mfma_f32_16x16x32_bf16 v[88:91], v[184:187], v[192:195], v[88:91]
	v_mfma_f32_16x16x32_bf16 v[84:87], v[176:179], v[200:203], v[84:87]
	v_mfma_f32_16x16x32_bf16 v[80:83], v[184:187], v[200:203], v[80:83]
	v_mfma_f32_16x16x32_bf16 v[76:79], v[176:179], v[208:211], v[76:79]
	v_mfma_f32_16x16x32_bf16 v[72:75], v[184:187], v[208:211], v[72:75]
	v_mfma_f32_16x16x32_bf16 v[68:71], v[176:179], v[216:219], v[68:71]
	v_mfma_f32_16x16x32_bf16 v[64:67], v[184:187], v[216:219], v[64:67]
	v_mfma_f32_16x16x32_bf16 v[92:95], v[180:183], v[196:199], v[92:95]
	v_mfma_f32_16x16x32_bf16 v[88:91], v[188:191], v[196:199], v[88:91]
	v_mfma_f32_16x16x32_bf16 v[84:87], v[180:183], v[204:207], v[84:87]
	v_mfma_f32_16x16x32_bf16 v[80:83], v[188:191], v[204:207], v[80:83]
	v_mfma_f32_16x16x32_bf16 v[76:79], v[180:183], v[212:215], v[76:79]
	v_mfma_f32_16x16x32_bf16 v[72:75], v[188:191], v[212:215], v[72:75]
	v_mfma_f32_16x16x32_bf16 v[68:71], v[180:183], v[220:223], v[68:71]
	v_mfma_f32_16x16x32_bf16 v[64:67], v[188:191], v[220:223], v[64:67]
	s_setprio 0
.Lp6k_4:
	s_barrier
	s_add_i32 s45, s45, 2
	s_add_u32 s6, s6, 0x100
	s_addc_u32 s7, s7, 0
	s_add_u32 s43, s43, 0x100
	s_addc_u32 s44, s44, 0
	s_cmp_gt_u32 s45, 13
	s_cbranch_scc0 .LBB0_743
	s_and_b64 vcc, exec, s[24:25]
	s_cbranch_vccz .LBB0_746
	s_barrier
